# GEMM main loop: dropped the blanket lgkmcnt(0) after each segment barrier, MFMA blocks now start on the progressive lgkmcnt(7..0) waits already present, bit-identical
# baseline (speedup 1.0000x reference)
; #define G_STAGE(P, RS, br, kt) do { const int _so = ((br) * G_K + (kt) * G_BK) * 2; \
;     __builtin_amdgcn_raw_ptr_buffer_load_lds(RS, (__attribute__((address_space(3))) unsigned*)((char*)(P) + tid * 16), 16, (int)voff0, _so, 0, 0); \
;     __builtin_amdgcn_raw_ptr_buffer_load_lds(RS, (__attribute__((address_space(3))) unsigned*)((char*)(P) + tid * 16 + 8192), 16, (int)voff1, _so, 0, 0); } while (0)
; #define G_LDA(dst, b, h) for (int m = 0; m < 4; ++m) for (int k = 0; k < 2; ++k) \
;     dst[m][k] = *reinterpret_cast<const bf16x8*>((char*)G_SA(b, h) + lds_byte(wr * 64 + m * 16 + fr, k * 32 + fq * 8))
; #define G_LDB(dst, b, h) for (int n = 0; n < 2; ++n) for (int k = 0; k < 2; ++k) \
;     dst[n][k] = *reinterpret_cast<const bf16x8*>((char*)G_SB(b, h) + lds_byte(wc * 32 + n * 16 + fr, k * 32 + fq * 8))
; #define G_MMA(ai, bj, At, Bt_) do { __builtin_amdgcn_s_setprio(1); \
;     for (int m = 0; m < 4; ++m) for (int n = 0; n < 2; ++n) for (int k = 0; k < 2; ++k) \
;       acc[ai][bj][m][n] = __builtin_amdgcn_mfma_f32_16x16x32_bf16(Bt_[n][k], At[m][k], acc[ai][bj][m][n], 0, 0, 0); \
;     __builtin_amdgcn_s_setprio(0); } while (0)
; #define WAIT_L(n) asm volatile("s_waitcnt lgkmcnt(" #n ")" ::: "memory")
; #define G_BAR __builtin_amdgcn_s_barrier()
; #define G_SCHED __builtin_amdgcn_sched_barrier(0)
; DEV void phase_gemm(const Params& p, int l, int mode) {
;     ...
;     for (int t = 0; t < nt - 2; t += 2) {
;       G_LDB(B0, 0, 0); G_SCHED; G_LDA(At, 0, 0); G_STAGE(G_SA(1, 1), A, brow + G_HALF, t + 1);
;       WAIT_L(8); G_BAR; WAIT_L(0); G_MMA(0, 0, At, B0); G_BAR; G_SCHED;
;       G_LDB(B1, 0, 1); G_STAGE(G_SB(0, 0), Bt, bcol, t + 2);
;       G_BAR; WAIT_L(0); G_MMA(0, 1, At, B1); G_BAR;
;       G_LDA(At, 0, 1); G_STAGE(G_SA(0, 0), A, brow, t + 2);
;       G_BAR; WAIT_L(0); G_MMA(1, 0, At, B0); G_BAR; G_SCHED;
.LBB0_211:
	ds_read_b128 v[128:131], v216
	ds_read_b128 v[132:135], v216 offset:1024
	ds_read_b128 v[136:139], v216 offset:2048
	ds_read_b128 v[140:143], v216 offset:3072
	s_add_i32 s12, s8, s11
	v_readfirstlane_b32 s19, v214
	s_add_i32 s13, s12, 0x40080
	s_mov_b32 m0, s19
	v_readfirstlane_b32 s19, v215
	ds_read_b128 v[144:147], v217
	ds_read_b128 v[148:151], v217 offset:1024
	ds_read_b128 v[152:155], v218
	ds_read_b128 v[156:159], v218 offset:1024
	ds_read_b128 v[168:171], v219
	ds_read_b128 v[172:175], v219 offset:1024
	ds_read_b128 v[176:179], v220
	ds_read_b128 v[180:183], v220 offset:1024
	buffer_load_dwordx4 v198, s[68:71], s13 offen lds
	s_mov_b32 m0, s19
	s_nop 0
	buffer_load_dwordx4 v199, s[68:71], s13 offen lds
	s_waitcnt lgkmcnt(8)
	s_barrier
	s_setprio 1
	s_waitcnt lgkmcnt(7)
	v_mfma_f32_16x16x32_bf16 v[124:127], v[128:131], v[144:147], v[124:127]
	v_mfma_f32_16x16x32_bf16 v[120:123], v[136:139], v[144:147], v[120:123]
	s_waitcnt lgkmcnt(5)
	v_mfma_f32_16x16x32_bf16 v[116:119], v[128:131], v[152:155], v[116:119]
	v_mfma_f32_16x16x32_bf16 v[112:115], v[136:139], v[152:155], v[112:115]
	s_waitcnt lgkmcnt(3)
	v_mfma_f32_16x16x32_bf16 v[108:111], v[128:131], v[168:171], v[108:111]
	v_mfma_f32_16x16x32_bf16 v[104:107], v[136:139], v[168:171], v[104:107]
	s_waitcnt lgkmcnt(1)
	v_mfma_f32_16x16x32_bf16 v[100:103], v[128:131], v[176:179], v[100:103]
	v_mfma_f32_16x16x32_bf16 v[96:99], v[136:139], v[176:179], v[96:99]
	v_mfma_f32_16x16x32_bf16 v[124:127], v[132:135], v[148:151], v[124:127]
	v_mfma_f32_16x16x32_bf16 v[120:123], v[140:143], v[148:151], v[120:123]
	v_mfma_f32_16x16x32_bf16 v[116:119], v[132:135], v[156:159], v[116:119]
	v_mfma_f32_16x16x32_bf16 v[112:115], v[140:143], v[156:159], v[112:115]
	v_mfma_f32_16x16x32_bf16 v[108:111], v[132:135], v[172:175], v[108:111]
	v_mfma_f32_16x16x32_bf16 v[104:107], v[140:143], v[172:175], v[104:107]
	s_waitcnt lgkmcnt(0)
	v_mfma_f32_16x16x32_bf16 v[100:103], v[132:135], v[180:183], v[100:103]
	v_mfma_f32_16x16x32_bf16 v[96:99], v[140:143], v[180:183], v[96:99]
	s_setprio 0
	s_barrier
	s_add_i32 s13, s9, s11
	v_readfirstlane_b32 s22, v200
	s_add_i32 s19, s13, 0x100
	s_mov_b32 s74, s70
	s_mov_b32 s75, s71
	s_mov_b32 m0, s22
	v_readfirstlane_b32 s22, v201
	ds_read_b128 v[224:227], v221
	ds_read_b128 v[228:231], v221 offset:1024
	ds_read_b128 v[232:235], v221 offset:2048
	ds_read_b128 v[236:239], v221 offset:3072
	buffer_load_dwordx4 v198, s[72:75], s19 offen lds
	s_mov_b32 m0, s22
	s_nop 0
	buffer_load_dwordx4 v199, s[72:75], s19 offen lds
	s_barrier
	s_setprio 1
	s_waitcnt lgkmcnt(3)
	v_mfma_f32_16x16x32_bf16 v[92:95], v[224:227], v[144:147], v[92:95]
	s_waitcnt lgkmcnt(1)
	v_mfma_f32_16x16x32_bf16 v[88:91], v[232:235], v[144:147], v[88:91]
	v_mfma_f32_16x16x32_bf16 v[84:87], v[224:227], v[152:155], v[84:87]
	v_mfma_f32_16x16x32_bf16 v[80:83], v[232:235], v[152:155], v[80:83]
	v_mfma_f32_16x16x32_bf16 v[76:79], v[224:227], v[168:171], v[76:79]
	v_mfma_f32_16x16x32_bf16 v[72:75], v[232:235], v[168:171], v[72:75]
	v_mfma_f32_16x16x32_bf16 v[68:71], v[224:227], v[176:179], v[68:71]
	v_mfma_f32_16x16x32_bf16 v[64:67], v[232:235], v[176:179], v[64:67]
	v_mfma_f32_16x16x32_bf16 v[92:95], v[228:231], v[148:151], v[92:95]
	s_waitcnt lgkmcnt(0)
	v_mfma_f32_16x16x32_bf16 v[88:91], v[236:239], v[148:151], v[88:91]
	v_mfma_f32_16x16x32_bf16 v[84:87], v[228:231], v[156:159], v[84:87]
	v_mfma_f32_16x16x32_bf16 v[80:83], v[236:239], v[156:159], v[80:83]
	v_mfma_f32_16x16x32_bf16 v[76:79], v[228:231], v[172:175], v[76:79]
	v_mfma_f32_16x16x32_bf16 v[72:75], v[236:239], v[172:175], v[72:75]
	v_mfma_f32_16x16x32_bf16 v[68:71], v[228:231], v[180:183], v[68:71]
	v_mfma_f32_16x16x32_bf16 v[64:67], v[236:239], v[180:183], v[64:67]
	s_setprio 0
	v_readfirstlane_b32 s22, v202
	s_add_i32 s19, s12, 0x100
	s_mov_b32 m0, s22
	v_readfirstlane_b32 s22, v203
	s_barrier
	ds_read_b128 v[144:147], v217 offset:16384
	ds_read_b128 v[148:151], v217 offset:17408
	ds_read_b128 v[152:155], v218 offset:16384
	ds_read_b128 v[156:159], v218 offset:17408
	ds_read_b128 v[168:171], v219 offset:16384
	ds_read_b128 v[172:175], v219 offset:17408
	ds_read_b128 v[176:179], v220 offset:16384
	ds_read_b128 v[180:183], v220 offset:17408
	buffer_load_dwordx4 v198, s[68:71], s19 offen lds
	s_mov_b32 m0, s22
	s_nop 0
	buffer_load_dwordx4 v199, s[68:71], s19 offen lds
	s_barrier
	s_setprio 1
	s_waitcnt lgkmcnt(7)
	v_mfma_f32_16x16x32_bf16 v[60:63], v[128:131], v[144:147], v[60:63]
	v_mfma_f32_16x16x32_bf16 v[56:59], v[136:139], v[144:147], v[56:59]
	s_waitcnt lgkmcnt(5)
	v_mfma_f32_16x16x32_bf16 v[52:55], v[128:131], v[152:155], v[52:55]
	v_mfma_f32_16x16x32_bf16 v[48:51], v[136:139], v[152:155], v[48:51]
	s_waitcnt lgkmcnt(3)
	v_mfma_f32_16x16x32_bf16 v[44:47], v[128:131], v[168:171], v[44:47]
	v_mfma_f32_16x16x32_bf16 v[40:43], v[136:139], v[168:171], v[40:43]
	s_waitcnt lgkmcnt(1)
	v_mfma_f32_16x16x32_bf16 v[36:39], v[128:131], v[176:179], v[36:39]
	v_mfma_f32_16x16x32_bf16 v[32:35], v[136:139], v[176:179], v[32:35]
	v_mfma_f32_16x16x32_bf16 v[60:63], v[132:135], v[148:151], v[60:63]
	v_mfma_f32_16x16x32_bf16 v[56:59], v[140:143], v[148:151], v[56:59]
	v_mfma_f32_16x16x32_bf16 v[52:55], v[132:135], v[156:159], v[52:55]
	v_mfma_f32_16x16x32_bf16 v[48:51], v[140:143], v[156:159], v[48:51]
	v_mfma_f32_16x16x32_bf16 v[44:47], v[132:135], v[172:175], v[44:47]
	v_mfma_f32_16x16x32_bf16 v[40:43], v[140:143], v[172:175], v[40:43]
	s_waitcnt lgkmcnt(0)
	v_mfma_f32_16x16x32_bf16 v[36:39], v[132:135], v[180:183], v[36:39]
	v_mfma_f32_16x16x32_bf16 v[32:35], v[140:143], v[180:183], v[32:35]
	s_setprio 0
	s_barrier
; #define G_STAGE(P, RS, br, kt) do { const int _so = ((br) * G_K + (kt) * G_BK) * 2; \
;     __builtin_amdgcn_raw_ptr_buffer_load_lds(RS, (__attribute__((address_space(3))) unsigned*)((char*)(P) + tid * 16), 16, (int)voff0, _so, 0, 0); \
;     __builtin_amdgcn_raw_ptr_buffer_load_lds(RS, (__attribute__((address_space(3))) unsigned*)((char*)(P) + tid * 16 + 8192), 16, (int)voff1, _so, 0, 0); } while (0)
; #define G_LDA(dst, b, h) for (int m = 0; m < 4; ++m) for (int k = 0; k < 2; ++k) \
;     dst[m][k] = *reinterpret_cast<const bf16x8*>((char*)G_SA(b, h) + lds_byte(wr * 64 + m * 16 + fr, k * 32 + fq * 8))
; #define G_LDB(dst, b, h) for (int n = 0; n < 2; ++n) for (int k = 0; k < 2; ++k) \
;     dst[n][k] = *reinterpret_cast<const bf16x8*>((char*)G_SB(b, h) + lds_byte(wc * 32 + n * 16 + fr, k * 32 + fq * 8))
; #define G_MMA(ai, bj, At, Bt_) do { __builtin_amdgcn_s_setprio(1); \
;     for (int m = 0; m < 4; ++m) for (int n = 0; n < 2; ++n) for (int k = 0; k < 2; ++k) \
;       acc[ai][bj][m][n] = __builtin_amdgcn_mfma_f32_16x16x32_bf16(Bt_[n][k], At[m][k], acc[ai][bj][m][n], 0, 0, 0); \
;     __builtin_amdgcn_s_setprio(0); } while (0)
; #define WAIT_V(n) asm volatile("s_waitcnt vmcnt(" #n ")" ::: "memory")
; #define WAIT_L(n) asm volatile("s_waitcnt lgkmcnt(" #n ")" ::: "memory")
; #define G_BAR __builtin_amdgcn_s_barrier()
; #define G_SCHED __builtin_amdgcn_sched_barrier(0)
; DEV void phase_gemm(const Params& p, int l, int mode) {
;     ...
;       G_STAGE(G_SB(0, 1), Bt, bcol + G_HALF, t + 2);
;       WAIT_V(6); G_BAR; G_MMA(1, 1, At, B1); G_BAR;
;       G_LDB(B0, 1, 0); G_SCHED; G_LDA(At, 1, 0); G_STAGE(G_SA(0, 1), A, brow + G_HALF, t + 2);
;       WAIT_L(8); G_BAR; WAIT_L(0); G_MMA(0, 0, At, B0); G_BAR; G_SCHED;
;       G_LDB(B1, 1, 1); G_STAGE(G_SB(1, 0), Bt, bcol, t + 3);
;       G_BAR; WAIT_L(0); G_MMA(0, 1, At, B1); G_BAR;
;       G_LDA(At, 1, 1); G_STAGE(G_SA(1, 0), A, brow, t + 3);
	v_readfirstlane_b32 s22, v204
	s_add_i32 s19, s13, 0x40100
	s_mov_b32 m0, s22
	v_readfirstlane_b32 s22, v205
	buffer_load_dwordx4 v198, s[72:75], s19 offen lds
	s_mov_b32 m0, s22
	s_nop 0
	buffer_load_dwordx4 v199, s[72:75], s19 offen lds
	s_waitcnt vmcnt(6)
	s_barrier
	s_setprio 1
	v_mfma_f32_16x16x32_bf16 v[28:31], v[224:227], v[144:147], v[28:31]
	v_mfma_f32_16x16x32_bf16 v[24:27], v[232:235], v[144:147], v[24:27]
	v_mfma_f32_16x16x32_bf16 v[20:23], v[224:227], v[152:155], v[20:23]
	v_mfma_f32_16x16x32_bf16 v[16:19], v[232:235], v[152:155], v[16:19]
	v_mfma_f32_16x16x32_bf16 v[12:15], v[224:227], v[168:171], v[12:15]
	v_mfma_f32_16x16x32_bf16 v[8:11], v[232:235], v[168:171], v[8:11]
	v_mfma_f32_16x16x32_bf16 v[4:7], v[224:227], v[176:179], v[4:7]
	v_mfma_f32_16x16x32_bf16 v[0:3], v[232:235], v[176:179], v[0:3]
	v_mfma_f32_16x16x32_bf16 v[28:31], v[228:231], v[148:151], v[28:31]
	v_mfma_f32_16x16x32_bf16 v[24:27], v[236:239], v[148:151], v[24:27]
	v_mfma_f32_16x16x32_bf16 v[20:23], v[228:231], v[156:159], v[20:23]
	v_mfma_f32_16x16x32_bf16 v[16:19], v[236:239], v[156:159], v[16:19]
	v_mfma_f32_16x16x32_bf16 v[12:15], v[228:231], v[172:175], v[12:15]
	v_mfma_f32_16x16x32_bf16 v[8:11], v[236:239], v[172:175], v[8:11]
	v_mfma_f32_16x16x32_bf16 v[4:7], v[228:231], v[180:183], v[4:7]
	v_mfma_f32_16x16x32_bf16 v[0:3], v[236:239], v[180:183], v[0:3]
	s_setprio 0
	s_barrier
	ds_read_b128 v[128:131], v222
	ds_read_b128 v[132:135], v222 offset:1024
	ds_read_b128 v[136:139], v222 offset:2048
	ds_read_b128 v[140:143], v222 offset:3072
	v_readfirstlane_b32 s22, v206
	s_add_i32 s19, s12, 0x40100
	s_mov_b32 m0, s22
	v_readfirstlane_b32 s22, v207
	ds_read_b128 v[144:147], v217 offset:32768
	ds_read_b128 v[148:151], v217 offset:33792
	ds_read_b128 v[152:155], v218 offset:32768
	ds_read_b128 v[156:159], v218 offset:33792
	ds_read_b128 v[168:171], v219 offset:32768
	ds_read_b128 v[172:175], v219 offset:33792
	ds_read_b128 v[176:179], v220 offset:32768
	ds_read_b128 v[180:183], v220 offset:33792
	buffer_load_dwordx4 v198, s[68:71], s19 offen lds
	s_mov_b32 m0, s22
	s_nop 0
	buffer_load_dwordx4 v199, s[68:71], s19 offen lds
	s_waitcnt lgkmcnt(8)
	s_barrier
	s_setprio 1
	s_waitcnt lgkmcnt(7)
	v_mfma_f32_16x16x32_bf16 v[124:127], v[128:131], v[144:147], v[124:127]
	v_mfma_f32_16x16x32_bf16 v[120:123], v[136:139], v[144:147], v[120:123]
	s_waitcnt lgkmcnt(5)
	v_mfma_f32_16x16x32_bf16 v[116:119], v[128:131], v[152:155], v[116:119]
	v_mfma_f32_16x16x32_bf16 v[112:115], v[136:139], v[152:155], v[112:115]
	s_waitcnt lgkmcnt(3)
	v_mfma_f32_16x16x32_bf16 v[108:111], v[128:131], v[168:171], v[108:111]
	v_mfma_f32_16x16x32_bf16 v[104:107], v[136:139], v[168:171], v[104:107]
	s_waitcnt lgkmcnt(1)
	v_mfma_f32_16x16x32_bf16 v[100:103], v[128:131], v[176:179], v[100:103]
	v_mfma_f32_16x16x32_bf16 v[96:99], v[136:139], v[176:179], v[96:99]
	v_mfma_f32_16x16x32_bf16 v[124:127], v[132:135], v[148:151], v[124:127]
	v_mfma_f32_16x16x32_bf16 v[120:123], v[140:143], v[148:151], v[120:123]
	v_mfma_f32_16x16x32_bf16 v[116:119], v[132:135], v[156:159], v[116:119]
	v_mfma_f32_16x16x32_bf16 v[112:115], v[140:143], v[156:159], v[112:115]
	v_mfma_f32_16x16x32_bf16 v[108:111], v[132:135], v[172:175], v[108:111]
	v_mfma_f32_16x16x32_bf16 v[104:107], v[140:143], v[172:175], v[104:107]
	s_waitcnt lgkmcnt(0)
	v_mfma_f32_16x16x32_bf16 v[100:103], v[132:135], v[180:183], v[100:103]
	v_mfma_f32_16x16x32_bf16 v[96:99], v[140:143], v[180:183], v[96:99]
	s_setprio 0
	s_barrier
	v_readfirstlane_b32 s22, v208
	s_add_i32 s19, s13, 0x180
	s_mov_b32 m0, s22
	v_readfirstlane_b32 s22, v209
	ds_read_b128 v[224:227], v223
	ds_read_b128 v[228:231], v223 offset:1024
	ds_read_b128 v[232:235], v223 offset:2048
	ds_read_b128 v[236:239], v223 offset:3072
	buffer_load_dwordx4 v198, s[72:75], s19 offen lds
	s_mov_b32 m0, s22
	s_nop 0
	buffer_load_dwordx4 v199, s[72:75], s19 offen lds
	s_barrier
	s_setprio 1
	s_waitcnt lgkmcnt(3)
	v_mfma_f32_16x16x32_bf16 v[92:95], v[224:227], v[144:147], v[92:95]
	s_waitcnt lgkmcnt(1)
	v_mfma_f32_16x16x32_bf16 v[88:91], v[232:235], v[144:147], v[88:91]
	v_mfma_f32_16x16x32_bf16 v[84:87], v[224:227], v[152:155], v[84:87]
	v_mfma_f32_16x16x32_bf16 v[80:83], v[232:235], v[152:155], v[80:83]
	v_mfma_f32_16x16x32_bf16 v[76:79], v[224:227], v[168:171], v[76:79]
	v_mfma_f32_16x16x32_bf16 v[72:75], v[232:235], v[168:171], v[72:75]
	v_mfma_f32_16x16x32_bf16 v[68:71], v[224:227], v[176:179], v[68:71]
	v_mfma_f32_16x16x32_bf16 v[64:67], v[232:235], v[176:179], v[64:67]
	v_mfma_f32_16x16x32_bf16 v[92:95], v[228:231], v[148:151], v[92:95]
	s_waitcnt lgkmcnt(0)
	v_mfma_f32_16x16x32_bf16 v[88:91], v[236:239], v[148:151], v[88:91]
	v_mfma_f32_16x16x32_bf16 v[84:87], v[228:231], v[156:159], v[84:87]
	v_mfma_f32_16x16x32_bf16 v[80:83], v[236:239], v[156:159], v[80:83]
	v_mfma_f32_16x16x32_bf16 v[76:79], v[228:231], v[172:175], v[76:79]
	v_mfma_f32_16x16x32_bf16 v[72:75], v[236:239], v[172:175], v[72:75]
	v_mfma_f32_16x16x32_bf16 v[68:71], v[228:231], v[180:183], v[68:71]
	v_mfma_f32_16x16x32_bf16 v[64:67], v[236:239], v[180:183], v[64:67]
	s_setprio 0
	v_readfirstlane_b32 s19, v210
	s_addk_i32 s12, 0x180
	s_mov_b32 m0, s19
	v_readfirstlane_b32 s19, v211
	s_barrier
	ds_read_b128 v[144:147], v217 offset:49152
	ds_read_b128 v[148:151], v217 offset:50176
	ds_read_b128 v[152:155], v218 offset:49152
	ds_read_b128 v[156:159], v218 offset:50176
	ds_read_b128 v[168:171], v219 offset:49152
	ds_read_b128 v[172:175], v219 offset:50176
	ds_read_b128 v[176:179], v220 offset:49152
	ds_read_b128 v[180:183], v220 offset:50176
	buffer_load_dwordx4 v198, s[68:71], s12 offen lds
	s_mov_b32 m0, s19
	s_nop 0
	buffer_load_dwordx4 v199, s[68:71], s12 offen lds
	s_barrier
; #define G_STAGE(P, RS, br, kt) do { const int _so = ((br) * G_K + (kt) * G_BK) * 2; \
;     __builtin_amdgcn_raw_ptr_buffer_load_lds(RS, (__attribute__((address_space(3))) unsigned*)((char*)(P) + tid * 16), 16, (int)voff0, _so, 0, 0); \
;     __builtin_amdgcn_raw_ptr_buffer_load_lds(RS, (__attribute__((address_space(3))) unsigned*)((char*)(P) + tid * 16 + 8192), 16, (int)voff1, _so, 0, 0); } while (0)
; #define G_LDA(dst, b, h) for (int m = 0; m < 4; ++m) for (int k = 0; k < 2; ++k) \
;     dst[m][k] = *reinterpret_cast<const bf16x8*>((char*)G_SA(b, h) + lds_byte(wr * 64 + m * 16 + fr, k * 32 + fq * 8))
; #define G_LDB(dst, b, h) for (int n = 0; n < 2; ++n) for (int k = 0; k < 2; ++k) \
;     dst[n][k] = *reinterpret_cast<const bf16x8*>((char*)G_SB(b, h) + lds_byte(wc * 32 + n * 16 + fr, k * 32 + fq * 8))
; #define G_MMA(ai, bj, At, Bt_) do { __builtin_amdgcn_s_setprio(1); \
;     for (int m = 0; m < 4; ++m) for (int n = 0; n < 2; ++n) for (int k = 0; k < 2; ++k) \
;       acc[ai][bj][m][n] = __builtin_amdgcn_mfma_f32_16x16x32_bf16(Bt_[n][k], At[m][k], acc[ai][bj][m][n], 0, 0, 0); \
;     __builtin_amdgcn_s_setprio(0); } while (0)
; #define WAIT_V(n) asm volatile("s_waitcnt vmcnt(" #n ")" ::: "memory")
; #define WAIT_L(n) asm volatile("s_waitcnt lgkmcnt(" #n ")" ::: "memory")
; #define G_BAR __builtin_amdgcn_s_barrier()
; #define G_SCHED __builtin_amdgcn_sched_barrier(0)
; DEV void phase_gemm(const Params& p, int l, int mode) {
;     ...
;       G_BAR; WAIT_L(0); G_MMA(1, 0, At, B0); G_BAR; G_SCHED;
;       G_STAGE(G_SB(1, 1), Bt, bcol + G_HALF, t + 3);
;       WAIT_V(6); G_BAR; G_MMA(1, 1, At, B1); G_BAR;
;     }
;     { G_LDB(B0, 0, 0); G_LDA(At, 0, 0); G_STAGE(G_SA(1, 1), A, brow + G_HALF, nt - 1);
;       G_BAR; WAIT_L(0); G_MMA(0, 0, At, B0); G_BAR;
;       G_LDB(B1, 0, 1); G_BAR; WAIT_L(0); G_MMA(0, 1, At, B1); G_BAR;
;       G_LDA(At, 0, 1); WAIT_V(4); G_BAR; WAIT_L(0); G_MMA(1, 0, At, B0); G_MMA(1, 1, At, B1); G_BAR; }
	s_setprio 1
	s_waitcnt lgkmcnt(7)
	v_mfma_f32_16x16x32_bf16 v[60:63], v[128:131], v[144:147], v[60:63]
	v_mfma_f32_16x16x32_bf16 v[56:59], v[136:139], v[144:147], v[56:59]
	s_waitcnt lgkmcnt(5)
	v_mfma_f32_16x16x32_bf16 v[52:55], v[128:131], v[152:155], v[52:55]
	v_mfma_f32_16x16x32_bf16 v[48:51], v[136:139], v[152:155], v[48:51]
	s_waitcnt lgkmcnt(3)
	v_mfma_f32_16x16x32_bf16 v[44:47], v[128:131], v[168:171], v[44:47]
	v_mfma_f32_16x16x32_bf16 v[40:43], v[136:139], v[168:171], v[40:43]
	s_waitcnt lgkmcnt(1)
	v_mfma_f32_16x16x32_bf16 v[36:39], v[128:131], v[176:179], v[36:39]
	v_mfma_f32_16x16x32_bf16 v[32:35], v[136:139], v[176:179], v[32:35]
	v_mfma_f32_16x16x32_bf16 v[60:63], v[132:135], v[148:151], v[60:63]
	v_mfma_f32_16x16x32_bf16 v[56:59], v[140:143], v[148:151], v[56:59]
	v_mfma_f32_16x16x32_bf16 v[52:55], v[132:135], v[156:159], v[52:55]
	v_mfma_f32_16x16x32_bf16 v[48:51], v[140:143], v[156:159], v[48:51]
	v_mfma_f32_16x16x32_bf16 v[44:47], v[132:135], v[172:175], v[44:47]
	v_mfma_f32_16x16x32_bf16 v[40:43], v[140:143], v[172:175], v[40:43]
	s_waitcnt lgkmcnt(0)
	v_mfma_f32_16x16x32_bf16 v[36:39], v[132:135], v[180:183], v[36:39]
	v_mfma_f32_16x16x32_bf16 v[32:35], v[140:143], v[180:183], v[32:35]
	s_setprio 0
	s_barrier
	v_readfirstlane_b32 s12, v212
	s_add_i32 s13, s13, 0x40180
	s_mov_b32 m0, s12
	v_readfirstlane_b32 s12, v213
	buffer_load_dwordx4 v198, s[72:75], s13 offen lds
	s_mov_b32 m0, s12
	s_nop 0
	buffer_load_dwordx4 v199, s[72:75], s13 offen lds
	s_waitcnt vmcnt(6)
	s_barrier
	s_setprio 1
	v_mfma_f32_16x16x32_bf16 v[28:31], v[224:227], v[144:147], v[28:31]
	v_mfma_f32_16x16x32_bf16 v[24:27], v[232:235], v[144:147], v[24:27]
	v_mfma_f32_16x16x32_bf16 v[20:23], v[224:227], v[152:155], v[20:23]
	v_mfma_f32_16x16x32_bf16 v[16:19], v[232:235], v[152:155], v[16:19]
	v_mfma_f32_16x16x32_bf16 v[12:15], v[224:227], v[168:171], v[12:15]
	v_mfma_f32_16x16x32_bf16 v[8:11], v[232:235], v[168:171], v[8:11]
	v_mfma_f32_16x16x32_bf16 v[4:7], v[224:227], v[176:179], v[4:7]
	v_mfma_f32_16x16x32_bf16 v[0:3], v[232:235], v[176:179], v[0:3]
	v_mfma_f32_16x16x32_bf16 v[28:31], v[228:231], v[148:151], v[28:31]
	v_mfma_f32_16x16x32_bf16 v[24:27], v[236:239], v[148:151], v[24:27]
	v_mfma_f32_16x16x32_bf16 v[20:23], v[228:231], v[156:159], v[20:23]
	v_mfma_f32_16x16x32_bf16 v[16:19], v[236:239], v[156:159], v[16:19]
	v_mfma_f32_16x16x32_bf16 v[12:15], v[228:231], v[172:175], v[12:15]
	v_mfma_f32_16x16x32_bf16 v[8:11], v[236:239], v[172:175], v[8:11]
	v_mfma_f32_16x16x32_bf16 v[4:7], v[228:231], v[180:183], v[4:7]
	v_mfma_f32_16x16x32_bf16 v[0:3], v[236:239], v[180:183], v[0:3]
	s_setprio 0
	s_add_i32 s10, s10, 2
	s_addk_i32 s11, 0x100
	s_cmp_lt_u32 s10, 12
	s_barrier
	s_cbranch_scc1 .LBB0_211
	v_readfirstlane_b32 s9, v214
	s_add_i32 s8, s8, 0x40780
	s_mov_b32 m0, s9
	v_readfirstlane_b32 s9, v215
	ds_read_b128 v[128:131], v216
	ds_read_b128 v[132:135], v216 offset:1024
	ds_read_b128 v[136:139], v216 offset:2048
	ds_read_b128 v[140:143], v216 offset:3072
	ds_read_b128 v[144:147], v217
	ds_read_b128 v[148:151], v217 offset:1024
	ds_read_b128 v[152:155], v218
	ds_read_b128 v[156:159], v218 offset:1024
	ds_read_b128 v[168:171], v219
	ds_read_b128 v[172:175], v219 offset:1024
	ds_read_b128 v[176:179], v220
	ds_read_b128 v[180:183], v220 offset:1024
	buffer_load_dwordx4 v198, s[68:71], s8 offen lds
	s_mov_b32 m0, s9
	s_nop 0
	buffer_load_dwordx4 v199, s[68:71], s8 offen lds
	s_barrier
	s_setprio 1
	s_waitcnt lgkmcnt(7)
	v_mfma_f32_16x16x32_bf16 v[124:127], v[128:131], v[144:147], v[124:127]
	s_waitcnt lgkmcnt(5)
	v_mfma_f32_16x16x32_bf16 v[116:119], v[128:131], v[152:155], v[116:119]
	s_waitcnt lgkmcnt(3)
	v_mfma_f32_16x16x32_bf16 v[108:111], v[128:131], v[168:171], v[108:111]
	v_mfma_f32_16x16x32_bf16 v[104:107], v[136:139], v[168:171], v[104:107]
	s_waitcnt lgkmcnt(1)
	v_mfma_f32_16x16x32_bf16 v[100:103], v[128:131], v[176:179], v[100:103]
	v_mfma_f32_16x16x32_bf16 v[96:99], v[136:139], v[176:179], v[96:99]
	v_mfma_f32_16x16x32_bf16 v[124:127], v[132:135], v[148:151], v[124:127]
	v_mfma_f32_16x16x32_bf16 v[120:123], v[136:139], v[144:147], v[120:123]
	v_mfma_f32_16x16x32_bf16 v[116:119], v[132:135], v[156:159], v[116:119]
	v_mfma_f32_16x16x32_bf16 v[112:115], v[136:139], v[152:155], v[112:115]
	v_mfma_f32_16x16x32_bf16 v[108:111], v[132:135], v[172:175], v[108:111]
	v_mfma_f32_16x16x32_bf16 v[104:107], v[140:143], v[172:175], v[104:107]
	s_waitcnt lgkmcnt(0)
	v_mfma_f32_16x16x32_bf16 v[100:103], v[132:135], v[180:183], v[100:103]
	v_mfma_f32_16x16x32_bf16 v[96:99], v[140:143], v[180:183], v[96:99]
	v_mfma_f32_16x16x32_bf16 v[224:227], v[140:143], v[148:151], v[120:123]
	v_mfma_f32_16x16x32_bf16 v[228:231], v[140:143], v[156:159], v[112:115]
	s_setprio 0
	s_barrier
	s_nop 0
	ds_read_b128 v[112:115], v221
	ds_read_b128 v[120:123], v221 offset:1024
	ds_read_b128 v[232:235], v221 offset:2048
	ds_read_b128 v[236:239], v221 offset:3072
	s_barrier
	s_setprio 1
	s_waitcnt lgkmcnt(3)
	v_mfma_f32_16x16x32_bf16 v[92:95], v[112:115], v[144:147], v[92:95]
	v_mfma_f32_16x16x32_bf16 v[84:87], v[112:115], v[152:155], v[84:87]
	v_mfma_f32_16x16x32_bf16 v[76:79], v[112:115], v[168:171], v[76:79]
	v_mfma_f32_16x16x32_bf16 v[68:71], v[112:115], v[176:179], v[68:71]
	s_waitcnt lgkmcnt(2)
	v_mfma_f32_16x16x32_bf16 v[92:95], v[120:123], v[148:151], v[92:95]
	s_waitcnt lgkmcnt(1)
	v_mfma_f32_16x16x32_bf16 v[88:91], v[232:235], v[144:147], v[88:91]
	v_mfma_f32_16x16x32_bf16 v[84:87], v[120:123], v[156:159], v[84:87]
	v_mfma_f32_16x16x32_bf16 v[80:83], v[232:235], v[152:155], v[80:83]
	v_mfma_f32_16x16x32_bf16 v[76:79], v[120:123], v[172:175], v[76:79]
	v_mfma_f32_16x16x32_bf16 v[72:75], v[232:235], v[168:171], v[72:75]
	v_mfma_f32_16x16x32_bf16 v[68:71], v[120:123], v[180:183], v[68:71]
	v_mfma_f32_16x16x32_bf16 v[64:67], v[232:235], v[176:179], v[64:67]
	s_waitcnt lgkmcnt(0)
	v_mfma_f32_16x16x32_bf16 v[144:147], v[236:239], v[148:151], v[88:91]
	v_mfma_f32_16x16x32_bf16 v[148:151], v[236:239], v[156:159], v[80:83]
	v_mfma_f32_16x16x32_bf16 v[152:155], v[236:239], v[172:175], v[72:75]
	v_mfma_f32_16x16x32_bf16 v[156:159], v[236:239], v[180:183], v[64:67]
	s_setprio 0
	s_barrier
; #define G_LDA(dst, b, h) for (int m = 0; m < 4; ++m) for (int k = 0; k < 2; ++k) \
;     dst[m][k] = *reinterpret_cast<const bf16x8*>((char*)G_SA(b, h) + lds_byte(wr * 64 + m * 16 + fr, k * 32 + fq * 8))
; #define G_LDB(dst, b, h) for (int n = 0; n < 2; ++n) for (int k = 0; k < 2; ++k) \
;     dst[n][k] = *reinterpret_cast<const bf16x8*>((char*)G_SB(b, h) + lds_byte(wc * 32 + n * 16 + fr, k * 32 + fq * 8))
; #define G_MMA(ai, bj, At, Bt_) do { __builtin_amdgcn_s_setprio(1); \
;     for (int m = 0; m < 4; ++m) for (int n = 0; n < 2; ++n) for (int k = 0; k < 2; ++k) \
;       acc[ai][bj][m][n] = __builtin_amdgcn_mfma_f32_16x16x32_bf16(Bt_[n][k], At[m][k], acc[ai][bj][m][n], 0, 0, 0); \
;     __builtin_amdgcn_s_setprio(0); } while (0)
; #define WAIT_V(n) asm volatile("s_waitcnt vmcnt(" #n ")" ::: "memory")
; #define WAIT_L(n) asm volatile("s_waitcnt lgkmcnt(" #n ")" ::: "memory")
; #define G_BAR __builtin_amdgcn_s_barrier()
; DEV void phase_gemm(const Params& p, int l, int mode) {
;     ...
;       G_LDB(B1, 0, 1); G_BAR; WAIT_L(0); G_MMA(0, 1, At, B1); G_BAR;
;       G_LDA(At, 0, 1); WAIT_V(4); G_BAR; WAIT_L(0); G_MMA(1, 0, At, B0); G_MMA(1, 1, At, B1); G_BAR; }
;     { G_LDB(B0, 1, 0); G_LDA(At, 1, 0); WAIT_V(2); G_BAR; WAIT_L(0); G_MMA(0, 0, At, B0); G_BAR;
	s_nop 0
	ds_read_b128 v[64:67], v217 offset:16384
	ds_read_b128 v[72:75], v217 offset:17408
	ds_read_b128 v[80:83], v218 offset:16384
	ds_read_b128 v[88:91], v218 offset:17408
	ds_read_b128 v[168:171], v219 offset:16384
	ds_read_b128 v[172:175], v219 offset:17408
	ds_read_b128 v[176:179], v220 offset:16384
	ds_read_b128 v[180:183], v220 offset:17408
	s_waitcnt vmcnt(4)
	s_barrier
	s_setprio 1
	s_waitcnt lgkmcnt(7)
	v_mfma_f32_16x16x32_bf16 v[60:63], v[128:131], v[64:67], v[60:63]
	v_mfma_f32_16x16x32_bf16 v[56:59], v[136:139], v[64:67], v[56:59]
	s_waitcnt lgkmcnt(5)
	v_mfma_f32_16x16x32_bf16 v[52:55], v[128:131], v[80:83], v[52:55]
	s_waitcnt lgkmcnt(3)
	v_mfma_f32_16x16x32_bf16 v[44:47], v[128:131], v[168:171], v[44:47]
	s_waitcnt lgkmcnt(1)
	v_mfma_f32_16x16x32_bf16 v[36:39], v[128:131], v[176:179], v[36:39]
	v_mfma_f32_16x16x32_bf16 v[60:63], v[132:135], v[72:75], v[60:63]
	v_mfma_f32_16x16x32_bf16 v[240:243], v[140:143], v[72:75], v[56:59]
	v_mfma_f32_16x16x32_bf16 v[52:55], v[132:135], v[88:91], v[52:55]
	v_mfma_f32_16x16x32_bf16 v[48:51], v[136:139], v[80:83], v[48:51]
	v_mfma_f32_16x16x32_bf16 v[44:47], v[132:135], v[172:175], v[44:47]
	v_mfma_f32_16x16x32_bf16 v[40:43], v[136:139], v[168:171], v[40:43]
	s_waitcnt lgkmcnt(0)
	v_mfma_f32_16x16x32_bf16 v[36:39], v[132:135], v[180:183], v[36:39]
	v_mfma_f32_16x16x32_bf16 v[32:35], v[136:139], v[176:179], v[32:35]
	v_mfma_f32_16x16x32_bf16 v[244:247], v[140:143], v[88:91], v[48:51]
	v_mfma_f32_16x16x32_bf16 v[248:251], v[140:143], v[172:175], v[40:43]
	v_mfma_f32_16x16x32_bf16 v[128:131], v[140:143], v[180:183], v[32:35]
	s_setprio 0
	s_setprio 1
	v_mfma_f32_16x16x32_bf16 v[12:15], v[112:115], v[168:171], v[12:15]
	v_mfma_f32_16x16x32_bf16 v[4:7], v[112:115], v[176:179], v[4:7]
	v_mfma_f32_16x16x32_bf16 v[28:31], v[112:115], v[64:67], v[28:31]
	v_mfma_f32_16x16x32_bf16 v[24:27], v[232:235], v[64:67], v[24:27]
	v_mfma_f32_16x16x32_bf16 v[20:23], v[112:115], v[80:83], v[20:23]
	v_mfma_f32_16x16x32_bf16 v[16:19], v[232:235], v[80:83], v[16:19]
	v_mfma_f32_16x16x32_bf16 v[12:15], v[120:123], v[172:175], v[12:15]
	v_mfma_f32_16x16x32_bf16 v[8:11], v[232:235], v[168:171], v[8:11]
	v_mfma_f32_16x16x32_bf16 v[4:7], v[120:123], v[180:183], v[4:7]
	v_mfma_f32_16x16x32_bf16 v[0:3], v[232:235], v[176:179], v[0:3]
	v_mfma_f32_16x16x32_bf16 v[132:135], v[120:123], v[72:75], v[28:31]
	v_mfma_f32_16x16x32_bf16 v[136:139], v[236:239], v[72:75], v[24:27]
	v_mfma_f32_16x16x32_bf16 v[140:143], v[120:123], v[88:91], v[20:23]
	v_mfma_f32_16x16x32_bf16 v[184:187], v[236:239], v[88:91], v[16:19]
	v_mfma_f32_16x16x32_bf16 v[168:171], v[236:239], v[172:175], v[8:11]
	v_mfma_f32_16x16x32_bf16 v[172:175], v[236:239], v[180:183], v[0:3]
	s_setprio 0
	s_barrier
	ds_read_b128 v[20:23], v222
	ds_read_b128 v[28:31], v222 offset:1024
	ds_read_b128 v[176:179], v222 offset:2048
	ds_read_b128 v[180:183], v222 offset:3072
	ds_read_b128 v[0:3], v217 offset:32768
	ds_read_b128 v[8:11], v217 offset:33792
	ds_read_b128 v[32:35], v218 offset:32768
	ds_read_b128 v[40:43], v218 offset:33792
	ds_read_b128 v[232:235], v219 offset:32768
	ds_read_b128 v[236:239], v219 offset:33792
	ds_read_b128 v[192:195], v220 offset:32768
	ds_read_b128 v[164:167], v220 offset:33792
	s_waitcnt vmcnt(2)
	s_barrier
	s_setprio 1
	s_waitcnt lgkmcnt(7)
	v_mfma_f32_16x16x32_bf16 v[16:19], v[20:23], v[0:3], v[124:127]
	s_waitcnt lgkmcnt(6)
	v_mfma_f32_16x16x32_bf16 v[120:123], v[28:31], v[8:11], v[16:19]
	v_mfma_f32_16x16x32_bf16 v[16:19], v[176:179], v[0:3], v[224:227]
	v_mfma_f32_16x16x32_bf16 v[112:115], v[180:183], v[8:11], v[16:19]
	s_waitcnt lgkmcnt(5)
	v_mfma_f32_16x16x32_bf16 v[16:19], v[20:23], v[32:35], v[116:119]
	s_waitcnt lgkmcnt(4)
	v_mfma_f32_16x16x32_bf16 v[88:91], v[28:31], v[40:43], v[16:19]
	v_mfma_f32_16x16x32_bf16 v[16:19], v[176:179], v[32:35], v[228:231]
	v_mfma_f32_16x16x32_bf16 v[80:83], v[180:183], v[40:43], v[16:19]
	s_waitcnt lgkmcnt(3)
	v_mfma_f32_16x16x32_bf16 v[16:19], v[20:23], v[232:235], v[108:111]
	s_waitcnt lgkmcnt(2)
	v_mfma_f32_16x16x32_bf16 v[108:111], v[28:31], v[236:239], v[16:19]
	v_mfma_f32_16x16x32_bf16 v[16:19], v[176:179], v[232:235], v[104:107]
	v_mfma_f32_16x16x32_bf16 v[56:59], v[180:183], v[236:239], v[16:19]
	s_waitcnt lgkmcnt(1)
	v_mfma_f32_16x16x32_bf16 v[16:19], v[20:23], v[192:195], v[100:103]
	s_waitcnt lgkmcnt(0)
	v_mfma_f32_16x16x32_bf16 v[48:51], v[28:31], v[164:167], v[16:19]
	v_mfma_f32_16x16x32_bf16 v[16:19], v[176:179], v[192:195], v[96:99]
	v_mfma_f32_16x16x32_bf16 v[24:27], v[180:183], v[164:167], v[16:19]
	s_setprio 0
	s_barrier
; #define G_LDA(dst, b, h) for (int m = 0; m < 4; ++m) for (int k = 0; k < 2; ++k) \
;     dst[m][k] = *reinterpret_cast<const bf16x8*>((char*)G_SA(b, h) + lds_byte(wr * 64 + m * 16 + fr, k * 32 + fq * 8))
; #define G_LDB(dst, b, h) for (int n = 0; n < 2; ++n) for (int k = 0; k < 2; ++k) \
;     dst[n][k] = *reinterpret_cast<const bf16x8*>((char*)G_SB(b, h) + lds_byte(wc * 32 + n * 16 + fr, k * 32 + fq * 8))
; #define G_MMA(ai, bj, At, Bt_) do { __builtin_amdgcn_s_setprio(1); \
;     for (int m = 0; m < 4; ++m) for (int n = 0; n < 2; ++n) for (int k = 0; k < 2; ++k) \
;       acc[ai][bj][m][n] = __builtin_amdgcn_mfma_f32_16x16x32_bf16(Bt_[n][k], At[m][k], acc[ai][bj][m][n], 0, 0, 0); \
;     __builtin_amdgcn_s_setprio(0); } while (0)
; #define WAIT_V(n) asm volatile("s_waitcnt vmcnt(" #n ")" ::: "memory")
; #define WAIT_L(n) asm volatile("s_waitcnt lgkmcnt(" #n ")" ::: "memory")
; #define G_BAR __builtin_amdgcn_s_barrier()
; DEV void phase_gemm(const Params& p, int l, int mode) {
;     ...
;     { G_LDB(B0, 1, 0); G_LDA(At, 1, 0); WAIT_V(2); G_BAR; WAIT_L(0); G_MMA(0, 0, At, B0); G_BAR;
;       G_LDB(B1, 1, 1); WAIT_V(0); G_BAR; WAIT_L(0); G_MMA(0, 1, At, B1); G_BAR;
;       G_LDA(At, 1, 1); G_BAR; WAIT_L(0); G_MMA(1, 0, At, B0); G_MMA(1, 1, At, B1); G_BAR; }
;     if (wr == 0) G_BAR;
	ds_read_b128 v[224:227], v223
	ds_read_b128 v[228:231], v223 offset:1024
	ds_read_b128 v[188:191], v223 offset:2048
	s_nop 1
	ds_read_b128 v[16:19], v223 offset:3072
	s_waitcnt vmcnt(0)
	s_barrier
	s_setprio 1
	s_waitcnt lgkmcnt(3)
	v_mfma_f32_16x16x32_bf16 v[64:67], v[224:227], v[0:3], v[92:95]
	s_waitcnt lgkmcnt(1)
	v_mfma_f32_16x16x32_bf16 v[0:3], v[188:191], v[0:3], v[144:147]
	s_waitcnt lgkmcnt(0)
	v_mfma_f32_16x16x32_bf16 v[96:99], v[16:19], v[8:11], v[0:3]
	v_mfma_f32_16x16x32_bf16 v[0:3], v[224:227], v[32:35], v[84:87]
	v_mfma_f32_16x16x32_bf16 v[72:75], v[228:231], v[40:43], v[0:3]
	v_mfma_f32_16x16x32_bf16 v[0:3], v[188:191], v[32:35], v[148:151]
	v_mfma_f32_16x16x32_bf16 v[104:107], v[228:231], v[8:11], v[64:67]
	v_mfma_f32_16x16x32_bf16 v[64:67], v[16:19], v[40:43], v[0:3]
	v_mfma_f32_16x16x32_bf16 v[0:3], v[224:227], v[232:235], v[76:79]
	v_mfma_f32_16x16x32_bf16 v[40:43], v[228:231], v[236:239], v[0:3]
	v_mfma_f32_16x16x32_bf16 v[0:3], v[188:191], v[232:235], v[152:155]
	v_mfma_f32_16x16x32_bf16 v[32:35], v[16:19], v[236:239], v[0:3]
	v_mfma_f32_16x16x32_bf16 v[0:3], v[224:227], v[192:195], v[68:71]
	v_mfma_f32_16x16x32_bf16 v[8:11], v[228:231], v[164:167], v[0:3]
	v_mfma_f32_16x16x32_bf16 v[0:3], v[188:191], v[192:195], v[156:159]
	v_mfma_f32_16x16x32_bf16 v[0:3], v[16:19], v[164:167], v[0:3]
	s_setprio 0
	s_barrier
	ds_read_b128 v[68:71], v217 offset:49152
	ds_read_b128 v[76:79], v217 offset:50176
	ds_read_b128 v[144:147], v218 offset:49152
	ds_read_b128 v[148:151], v218 offset:50176
	ds_read_b128 v[152:155], v219 offset:49152
	ds_read_b128 v[156:159], v219 offset:50176
	ds_read_b128 v[164:167], v220 offset:49152
	ds_read_b128 v[192:195], v220 offset:50176
	s_barrier
	s_setprio 1
	s_waitcnt lgkmcnt(7)
	v_mfma_f32_16x16x32_bf16 v[60:63], v[20:23], v[68:71], v[60:63]
	s_waitcnt lgkmcnt(6)
	v_mfma_f32_16x16x32_bf16 v[124:127], v[28:31], v[76:79], v[60:63]
	v_mfma_f32_16x16x32_bf16 v[60:63], v[176:179], v[68:71], v[240:243]
	s_waitcnt lgkmcnt(5)
	v_mfma_f32_16x16x32_bf16 v[52:55], v[20:23], v[144:147], v[52:55]
	s_waitcnt lgkmcnt(3)
	v_mfma_f32_16x16x32_bf16 v[44:47], v[20:23], v[152:155], v[44:47]
	s_waitcnt lgkmcnt(1)
	v_mfma_f32_16x16x32_bf16 v[20:23], v[20:23], v[164:167], v[36:39]
	v_mfma_f32_16x16x32_bf16 v[116:119], v[180:183], v[76:79], v[60:63]
	v_mfma_f32_16x16x32_bf16 v[92:95], v[28:31], v[148:151], v[52:55]
	v_mfma_f32_16x16x32_bf16 v[52:55], v[176:179], v[144:147], v[244:247]
	v_mfma_f32_16x16x32_bf16 v[60:63], v[28:31], v[156:159], v[44:47]
	v_mfma_f32_16x16x32_bf16 v[44:47], v[176:179], v[152:155], v[248:251]
	s_waitcnt lgkmcnt(0)
	v_mfma_f32_16x16x32_bf16 v[28:31], v[28:31], v[192:195], v[20:23]
	v_mfma_f32_16x16x32_bf16 v[20:23], v[176:179], v[164:167], v[128:131]
	v_mfma_f32_16x16x32_bf16 v[84:87], v[180:183], v[148:151], v[52:55]
	v_mfma_f32_16x16x32_bf16 v[52:55], v[180:183], v[156:159], v[44:47]
	v_mfma_f32_16x16x32_bf16 v[20:23], v[180:183], v[192:195], v[20:23]
	s_setprio 0
	s_setprio 1
	v_mfma_f32_16x16x32_bf16 v[36:39], v[224:227], v[68:71], v[132:135]
	v_mfma_f32_16x16x32_bf16 v[240:243], v[228:231], v[76:79], v[36:39]
	v_mfma_f32_16x16x32_bf16 v[36:39], v[188:191], v[68:71], v[136:139]
	v_mfma_f32_16x16x32_bf16 v[100:103], v[16:19], v[76:79], v[36:39]
	v_mfma_f32_16x16x32_bf16 v[36:39], v[224:227], v[144:147], v[140:143]
	v_mfma_f32_16x16x32_bf16 v[12:15], v[224:227], v[152:155], v[12:15]
	v_mfma_f32_16x16x32_bf16 v[76:79], v[228:231], v[148:151], v[36:39]
	v_mfma_f32_16x16x32_bf16 v[36:39], v[188:191], v[144:147], v[184:187]
	v_mfma_f32_16x16x32_bf16 v[44:47], v[228:231], v[156:159], v[12:15]
	v_mfma_f32_16x16x32_bf16 v[12:15], v[188:191], v[152:155], v[168:171]
	v_mfma_f32_16x16x32_bf16 v[4:7], v[224:227], v[164:167], v[4:7]
	v_mfma_f32_16x16x32_bf16 v[68:71], v[16:19], v[148:151], v[36:39]
	v_mfma_f32_16x16x32_bf16 v[36:39], v[16:19], v[156:159], v[12:15]
	v_mfma_f32_16x16x32_bf16 v[12:15], v[228:231], v[192:195], v[4:7]
	v_mfma_f32_16x16x32_bf16 v[4:7], v[188:191], v[164:167], v[172:175]
	v_mfma_f32_16x16x32_bf16 v[4:7], v[16:19], v[192:195], v[4:7]
	s_setprio 0
	s_barrier
	s_mov_b64 s[8:9], exec
	v_readlane_b32 s10, v255, 27
	v_readlane_b32 s11, v255, 28
	s_and_b64 s[10:11], s[8:9], s[10:11]
	s_mov_b64 exec, s[10:11]
	s_cbranch_execz .LBB0_214
	s_barrier
